# per-tile unit headers of the FFN-up and in-projection GEMMs: tile decode with scalar shift/mask instead of a float-division VALU chain and two v_readfirstlane
# baseline (speedup 1.0000x reference)
.LBB0_397:
	s_ashr_i32 s6, s8, 3
	s_add_i32 s6, s10, s6
	s_mul_hi_i32 s7, s6, 0x78787879
	s_lshr_b32 s8, s7, 31
	s_ashr_i32 s7, s7, 7
	s_add_i32 s7, s7, s8
	s_lshl_b32 s8, s7, 3
	s_sub_i32 s9, 0x41, s8
	s_min_u32 s9, s9, 8
	s_mov_b64 s[10:11], -1
	s_mul_i32 s7, s7, 0x110
	s_sub_i32 s7, s6, s7
	s_cmp_eq_u32 s9, 8
	s_cselect_b32 s6, 7, 0
	s_cselect_b32 s9, 3, 0
	s_and_b32 s6, s7, s6
	s_add_i32 s6, s8, s6
	s_lshr_b32 s7, s7, s9
	s_sext_i32_i16 s21, s7
	s_cmp_lt_i32 s21, 28
	s_cbranch_scc0 .LBB0_399
	s_ashr_i32 s7, s6, 31
	s_mov_b64 s[10:11], 0
	s_mov_b64 s[8:9], s[6:7]

.LBB0_1274:
	s_ashr_i32 s2, s4, 3
	s_add_i32 s2, s6, s2
	s_mul_hi_i32 s3, s2, 0x2e8ba2e9
	s_lshr_b32 s4, s3, 31
	s_ashr_i32 s3, s3, 5
	s_add_i32 s3, s3, s4
	s_lshl_b32 s4, s3, 3
	s_sub_i32 s5, 0x41, s4
	s_min_u32 s5, s5, 8
	s_mulk_i32 s3, 0xb0
	s_sub_i32 s6, s2, s3
	v_readlane_b32 s10, v252, 9
	s_cmp_eq_u32 s5, 8
	s_cselect_b32 s7, 3, 0
	s_cselect_b32 s2, 7, 0
	s_and_b32 s2, s6, s2
	s_add_i32 s2, s4, s2
	s_lshr_b32 s6, s6, s7
	s_ashr_i32 s3, s2, 31
	s_lshl_b64 s[4:5], s[2:3], 19
	v_readlane_b32 s11, v252, 10
	s_add_u32 s4, s10, s4
	s_sext_i32_i16 s35, s6
	s_addc_u32 s5, s11, s5
	s_bfe_i64 s[6:7], s[6:7], 0x100000
	s_lshl_b64 s[6:7], s[6:7], 19
	s_add_u32 s6, s24, s6
	s_addc_u32 s7, s25, s7
	s_mov_b64 s[10:11], s[4:5]
	s_mov_b64 s[12:13], s[6:7]
